# norm phases v2: contiguous row quads per wave, parameters kept in registers while the batch is unchanged, next quad's row loads issued before the current quad is reduced
# baseline (speedup 1.0000x reference)
; DI int get_tid() { int t = threadIdx.x; asm volatile("" : "+v"(t)); return t; }
; DI void phase_norm(const Params& p, int layer, int which  , int nrows) {
;   const int lane = get_tid() & 63, gw = blockIdx.x * 4 + (get_tid() >> 6), nw = gridDim.x * 4;
;   const float* g = (which == 0 ? p.norm1_g : p.norm2_g) + layer * D;
;   const float* mod = (const float*)(p.ws + OFF_MOD) + (size_t)layer * 9 * 6144;
;   bf16_t* H = (bf16_t*)(p.ws + OFF_H);
;   const bool first = (which == 0) && layer == 0;
;   for (int pr = gw; pr < (nrows >> 1); pr += nw) {
.Lnm_entry:
	v_writelane_b32 v254, s52, 0
	v_writelane_b32 v254, s53, 1
	v_writelane_b32 v254, s54, 2
	v_writelane_b32 v254, s55, 3
	v_writelane_b32 v254, s56, 4
	v_writelane_b32 v254, s57, 5
	v_writelane_b32 v254, s58, 6
	v_writelane_b32 v254, s59, 7
	v_writelane_b32 v254, s60, 8
	v_writelane_b32 v254, s61, 9
	v_writelane_b32 v254, s62, 10
	v_writelane_b32 v254, s63, 11
	v_writelane_b32 v254, s64, 12
	v_writelane_b32 v254, s65, 13
	v_writelane_b32 v254, s66, 14
	v_writelane_b32 v254, s67, 15
	v_writelane_b32 v254, s68, 16
	v_writelane_b32 v254, s69, 17
	v_writelane_b32 v254, s70, 18
	v_writelane_b32 v254, s71, 19
	v_writelane_b32 v254, s72, 20
	v_writelane_b32 v254, s73, 21
	v_writelane_b32 v254, s74, 22
	v_writelane_b32 v254, s75, 23
	v_writelane_b32 v254, s76, 24
	v_writelane_b32 v254, s77, 25
	v_writelane_b32 v254, s78, 26
	v_writelane_b32 v254, s79, 27
	v_writelane_b32 v254, s80, 28
	v_writelane_b32 v254, s81, 29
	v_writelane_b32 v254, s82, 30
	v_writelane_b32 v254, s83, 31
	v_writelane_b32 v254, s84, 32
	v_writelane_b32 v254, s85, 33
	v_writelane_b32 v254, s86, 34
	v_writelane_b32 v254, s87, 35
	v_writelane_b32 v254, s88, 36
	v_writelane_b32 v254, s89, 37
	v_writelane_b32 v254, s90, 38
	v_writelane_b32 v254, s91, 39
	s_mov_b32 s52, s100
	s_mov_b32 s53, s101
	v_lshrrev_b32_e32 v132, 6, v143
	v_readlane_b32 s0, v255, 0
	s_nop 0
	v_readfirstlane_b32 s1, v132
	s_nop 3
	s_lshl_b32 s0, s0, 2
	s_add_u32 s0, s0, s1
	s_movk_i32 s12, 512
	s_cmp_eq_u32 s52, 1
	s_cbranch_scc0 .Lnm_nq_1
	s_cmp_eq_u32 s53, 0
	s_cbranch_scc1 .Lnm_nq_1
	s_mov_b32 s12, 0
.Lnm_nq_1:
	s_cmp_lt_u32 s0, s12
	s_cbranch_scc1 .Lnm_five_2
	s_lshl_b32 s54, s0, 2
	s_add_u32 s54, s54, s12
	s_add_u32 s78, s54, 4
	s_branch .Lnm_qj_3
.Lnm_five_2:
	s_mul_i32 s54, s0, 5
	s_add_u32 s78, s54, 5

; DI void phase_norm(const Params& p, int layer, int which  , int nrows) {
;     ...
;   for (int pr = gw; pr < (nrows >> 1); pr += nw) {
;     const int row = pr * 2;
;     const float* xr0 = xold_ptr(p, layer, first, row);
;     const float* xr1 = xold_ptr(p, layer, first, row + 1);
;     const int b9 = row < NLAT ? (row >> 12) : 8;
;     float4 v[2][4];
;     float ss0 = 0.f, ss1 = 0.f;
; #pragma unroll
;     for (int i = 0; i < 4; ++i) {
;       typedef float f4ld __attribute__((ext_vector_type(4)));
;       const f4ld a_ = __builtin_nontemporal_load((const f4ld*)xr0 + lane + 64 * i), b_ = __builtin_nontemporal_load((const f4ld*)xr1 + lane + 64 * i);
;       v[0][i] = make_float4(a_[0], a_[1], a_[2], a_[3]); v[1][i] = make_float4(b_[0], b_[1], b_[2], b_[3]);
;     }
;     const float* sh = mod + b9 * 6144 + (which == 0 ? 0 : 3) * 1024;
;     const float* sc = sh + 1024;
;     float4 gg[4], s4[4], h4[4];
; #pragma unroll
;     for (int i = 0; i < 4; ++i) {
;       const int col = 4 * (lane + 64 * i);
;       gg[i] = *(const float4*)(g + col); s4[i] = *(const float4*)(sc + col); h4[i] = *(const float4*)(sh + col);
;     }
.Lnm_gj_6:
	s_waitcnt lgkmcnt(0)
	s_lshl_b32 s0, s53, 12
	s_add_u32 s68, s68, s0
	s_addc_u32 s69, s69, 0
	s_mul_i32 s0, s53, 221184
	s_mul_i32 s1, s52, 12288
	s_add_u32 s0, s0, s1
	s_add_u32 s0, s0, 0x1d300000
	s_add_u32 s70, s24, s0
	s_addc_u32 s71, s25, 0
	v_and_b32_e32 v132, 63, v143
	v_lshlrev_b32_e32 v152, 4, v132
	v_mov_b32_e32 v144, v152
	v_add_u32_e32 v145, 0x1000, v152
	v_add_u32_e32 v146, 0x2000, v152
	v_add_u32_e32 v147, 0x3000, v152
	v_lshrrev_b32_e32 v133, 3, v132
	s_mov_b32 s0, 0x220000
	v_mul_lo_u32 v133, v133, s0
	v_and_b32_e32 v134, 7, v132
	v_lshl_add_u32 v148, v134, 3, v133
	v_add_u32_e32 v149, 0x1100000, v148
	v_add_u32_e32 v150, 0x1100000, v149
	v_add_u32_e32 v151, 0x1100000, v150
	v_mov_b32_e32 v153, 0x358637bd
	s_mov_b32 s79, -1
	s_lshl_b32 s0, s54, 2
	s_cmp_lt_u32 s0, 0x8000
	s_cbranch_scc0 .Lnm_ctx_8
	s_lshl_b32 s0, s0, 12
	s_add_u32 s64, s60, s0
	s_addc_u32 s65, s61, 0
	s_branch .Lnm_j_9
.Lnm_ctx_8:
	s_sub_u32 s0, s0, 0x8000
	s_lshl_b32 s0, s0, 12
	s_add_u32 s64, s62, s0
	s_addc_u32 s65, s63, 0
.Lnm_j_9:
	global_load_dwordx4 v[0:3], v144, s[64:65] offset:0 nt
	global_load_dwordx4 v[4:7], v144, s[64:65] offset:1024 nt
	global_load_dwordx4 v[8:11], v144, s[64:65] offset:2048 nt
	global_load_dwordx4 v[12:15], v144, s[64:65] offset:3072 nt
	global_load_dwordx4 v[16:19], v145, s[64:65] offset:0 nt
	global_load_dwordx4 v[20:23], v145, s[64:65] offset:1024 nt
	global_load_dwordx4 v[24:27], v145, s[64:65] offset:2048 nt
	global_load_dwordx4 v[28:31], v145, s[64:65] offset:3072 nt
	global_load_dwordx4 v[32:35], v146, s[64:65] offset:0 nt
	global_load_dwordx4 v[36:39], v146, s[64:65] offset:1024 nt
	global_load_dwordx4 v[40:43], v146, s[64:65] offset:2048 nt
	global_load_dwordx4 v[44:47], v146, s[64:65] offset:3072 nt
	global_load_dwordx4 v[48:51], v147, s[64:65] offset:0 nt
	global_load_dwordx4 v[52:55], v147, s[64:65] offset:1024 nt
	global_load_dwordx4 v[56:59], v147, s[64:65] offset:2048 nt
	global_load_dwordx4 v[60:63], v147, s[64:65] offset:3072 nt
.Lnm_loop_10:
	s_lshl_b32 s57, s54, 2
	s_lshr_b32 s1, s57, 12
	s_min_u32 s1, s1, 8
	s_cmp_eq_u32 s1, s79
	s_cbranch_scc1 .Lnm_same_11
	s_mov_b32 s79, s1
	s_mul_i32 s1, s1, 24576
	s_add_u32 s72, s70, s1
	s_addc_u32 s73, s71, 0
	s_add_u32 s74, s72, 0x1000
	s_addc_u32 s75, s73, 0
	global_load_dwordx4 v[154:157], v152, s[68:69] offset:0
	global_load_dwordx4 v[158:161], v152, s[68:69] offset:1024
	global_load_dwordx4 v[162:165], v152, s[68:69] offset:2048
	global_load_dwordx4 v[166:169], v152, s[68:69] offset:3072
	global_load_dwordx4 v[214:217], v152, s[74:75] offset:0
	global_load_dwordx4 v[218:221], v152, s[74:75] offset:1024
	global_load_dwordx4 v[222:225], v152, s[74:75] offset:2048
	global_load_dwordx4 v[226:229], v152, s[74:75] offset:3072
	global_load_dwordx4 v[170:173], v152, s[72:73] offset:0
	global_load_dwordx4 v[174:177], v152, s[72:73] offset:1024
	global_load_dwordx4 v[178:181], v152, s[72:73] offset:2048
	global_load_dwordx4 v[182:185], v152, s[72:73] offset:3072
	s_waitcnt vmcnt(0)
	v_add_f32_e32 v214, 1.0, v214
	v_add_f32_e32 v215, 1.0, v215
	v_add_f32_e32 v216, 1.0, v216
	v_add_f32_e32 v217, 1.0, v217
	v_add_f32_e32 v218, 1.0, v218
	v_add_f32_e32 v219, 1.0, v219
	v_add_f32_e32 v220, 1.0, v220
	v_add_f32_e32 v221, 1.0, v221
	v_add_f32_e32 v222, 1.0, v222
	v_add_f32_e32 v223, 1.0, v223
	v_add_f32_e32 v224, 1.0, v224
	v_add_f32_e32 v225, 1.0, v225
	v_add_f32_e32 v226, 1.0, v226
	v_add_f32_e32 v227, 1.0, v227
	v_add_f32_e32 v228, 1.0, v228
	v_add_f32_e32 v229, 1.0, v229
	v_mul_f32_e32 v154, v154, v214
	v_mul_f32_e32 v155, v155, v215
	v_mul_f32_e32 v156, v156, v216
	v_mul_f32_e32 v157, v157, v217
	v_mul_f32_e32 v158, v158, v218
	v_mul_f32_e32 v159, v159, v219
	v_mul_f32_e32 v160, v160, v220
	v_mul_f32_e32 v161, v161, v221
	v_mul_f32_e32 v162, v162, v222
	v_mul_f32_e32 v163, v163, v223
	v_mul_f32_e32 v164, v164, v224
	v_mul_f32_e32 v165, v165, v225
	v_mul_f32_e32 v166, v166, v226
	v_mul_f32_e32 v167, v167, v227
	v_mul_f32_e32 v168, v168, v228
	v_mul_f32_e32 v169, v169, v229
.Lnm_same_11:
	s_add_u32 s80, s54, 1
	s_cmp_lt_u32 s80, s78
	s_cbranch_scc0 .Lnm_nonext_14
	s_lshl_b32 s0, s80, 2
	s_cmp_lt_u32 s0, 0x8000
	s_cbranch_scc0 .Lnm_ctx_16
	s_lshl_b32 s0, s0, 12
	s_add_u32 s64, s60, s0
	s_addc_u32 s65, s61, 0
	s_branch .Lnm_j_17

; DI void phase_norm(const Params& p, int layer, int which  , int nrows) {
;     ...
;     for (int i = 0; i < 4; ++i) {
;       typedef float f4ld __attribute__((ext_vector_type(4)));
;       const f4ld a_ = __builtin_nontemporal_load((const f4ld*)xr0 + lane + 64 * i), b_ = __builtin_nontemporal_load((const f4ld*)xr1 + lane + 64 * i);
;       v[0][i] = make_float4(a_[0], a_[1], a_[2], a_[3]); v[1][i] = make_float4(b_[0], b_[1], b_[2], b_[3]);
;     }
.Lnm_j_17:
	global_load_dwordx4 v[64:67], v144, s[64:65] offset:0 nt
	global_load_dwordx4 v[68:71], v144, s[64:65] offset:1024 nt
	global_load_dwordx4 v[72:75], v144, s[64:65] offset:2048 nt
	global_load_dwordx4 v[76:79], v144, s[64:65] offset:3072 nt
	global_load_dwordx4 v[80:83], v145, s[64:65] offset:0 nt
	global_load_dwordx4 v[84:87], v145, s[64:65] offset:1024 nt
	global_load_dwordx4 v[88:91], v145, s[64:65] offset:2048 nt
	global_load_dwordx4 v[92:95], v145, s[64:65] offset:3072 nt
	global_load_dwordx4 v[96:99], v146, s[64:65] offset:0 nt
	global_load_dwordx4 v[100:103], v146, s[64:65] offset:1024 nt
	global_load_dwordx4 v[104:107], v146, s[64:65] offset:2048 nt
	global_load_dwordx4 v[108:111], v146, s[64:65] offset:3072 nt
	global_load_dwordx4 v[112:115], v147, s[64:65] offset:0 nt
	global_load_dwordx4 v[116:119], v147, s[64:65] offset:1024 nt
	global_load_dwordx4 v[120:123], v147, s[64:65] offset:2048 nt
	global_load_dwordx4 v[124:127], v147, s[64:65] offset:3072 nt
	s_waitcnt vmcnt(16)
	s_branch .Lnm_nj_15

; DI unsigned pack2(float lo, float hi) { f32x2_t v = {lo, hi}; bf16x2_t r = __builtin_convertvector(v, bf16x2_t); return __builtin_bit_cast(unsigned, r); }
; DI void phase_norm(const Params& p, int layer, int which  , int nrows) {
;     ...
; #pragma unroll
;     for (int i = 0; i < 4; ++i) {
;       ss0 += v[0][i].x * v[0][i].x + v[0][i].y * v[0][i].y + v[0][i].z * v[0][i].z + v[0][i].w * v[0][i].w;
;       ss1 += v[1][i].x * v[1][i].x + v[1][i].y * v[1][i].y + v[1][i].z * v[1][i].z + v[1][i].w * v[1][i].w;
;     }
;     ss0 = wave_sum(ss0); ss1 = wave_sum(ss1);
;     const float rstd0 = rsqrtf(ss0 * (1.0f / D) + 1e-6f), rstd1 = rsqrtf(ss1 * (1.0f / D) + 1e-6f);
; #pragma unroll
;     for (int k = 0; k < 2; ++k) {
;       const float rstd = k == 0 ? rstd0 : rstd1;
; #pragma unroll
;       for (int i = 0; i < 4; ++i) {
;         const int col = 4 * (lane + 64 * i);
;         float y0 = v[k][i].x * rstd * gg[i].x * (1.f + s4[i].x) + h4[i].x;
;         float y1 = v[k][i].y * rstd * gg[i].y * (1.f + s4[i].y) + h4[i].y;
;         float y2 = v[k][i].z * rstd * gg[i].z * (1.f + s4[i].z) + h4[i].z;
;         float y3 = v[k][i].w * rstd * gg[i].w * (1.f + s4[i].w) + h4[i].w;
;         uint2 w; w.x = pack2(y0, y1); w.y = pack2(y2, y3);
;         *(uint2*)(H + (size_t)(row + k) * D + col) = w;
;       }
;     }
.Lnm_nj_15:
	s_lshl_b32 s0, s57, 6
	s_add_u32 s0, s0, 0x15980000
	s_add_u32 s66, s24, s0
	s_addc_u32 s67, s25, 0
	v_mul_f32_e32 v128, v0, v0
	v_fmac_f32_e32 v128, v1, v1
	v_fmac_f32_e32 v128, v2, v2
	v_fmac_f32_e32 v128, v3, v3
	v_fmac_f32_e32 v128, v4, v4
	v_fmac_f32_e32 v128, v5, v5
	v_fmac_f32_e32 v128, v6, v6
	v_fmac_f32_e32 v128, v7, v7
	v_fmac_f32_e32 v128, v8, v8
	v_fmac_f32_e32 v128, v9, v9
	v_fmac_f32_e32 v128, v10, v10
	v_fmac_f32_e32 v128, v11, v11
	v_fmac_f32_e32 v128, v12, v12
	v_fmac_f32_e32 v128, v13, v13
	v_fmac_f32_e32 v128, v14, v14
	v_fmac_f32_e32 v128, v15, v15
	v_mul_f32_e32 v129, v16, v16
	v_fmac_f32_e32 v129, v17, v17
	v_fmac_f32_e32 v129, v18, v18
	v_fmac_f32_e32 v129, v19, v19
	v_fmac_f32_e32 v129, v20, v20
	v_fmac_f32_e32 v129, v21, v21
	v_fmac_f32_e32 v129, v22, v22
	v_fmac_f32_e32 v129, v23, v23
	v_fmac_f32_e32 v129, v24, v24
	v_fmac_f32_e32 v129, v25, v25
	v_fmac_f32_e32 v129, v26, v26
	v_fmac_f32_e32 v129, v27, v27
	v_fmac_f32_e32 v129, v28, v28
	v_fmac_f32_e32 v129, v29, v29
	v_fmac_f32_e32 v129, v30, v30
	v_fmac_f32_e32 v129, v31, v31
	v_mul_f32_e32 v130, v32, v32
	v_fmac_f32_e32 v130, v33, v33
	v_fmac_f32_e32 v130, v34, v34
	v_fmac_f32_e32 v130, v35, v35
	v_fmac_f32_e32 v130, v36, v36
	v_fmac_f32_e32 v130, v37, v37
	v_fmac_f32_e32 v130, v38, v38
	v_fmac_f32_e32 v130, v39, v39
	v_fmac_f32_e32 v130, v40, v40
	v_fmac_f32_e32 v130, v41, v41
	v_fmac_f32_e32 v130, v42, v42
	v_fmac_f32_e32 v130, v43, v43
	v_fmac_f32_e32 v130, v44, v44
	v_fmac_f32_e32 v130, v45, v45
	v_fmac_f32_e32 v130, v46, v46
	v_fmac_f32_e32 v130, v47, v47
	v_mul_f32_e32 v131, v48, v48
	v_fmac_f32_e32 v131, v49, v49
	v_fmac_f32_e32 v131, v50, v50
	v_fmac_f32_e32 v131, v51, v51
	v_fmac_f32_e32 v131, v52, v52
	v_fmac_f32_e32 v131, v53, v53
	v_fmac_f32_e32 v131, v54, v54
	v_fmac_f32_e32 v131, v55, v55
	v_fmac_f32_e32 v131, v56, v56
	v_fmac_f32_e32 v131, v57, v57
	v_fmac_f32_e32 v131, v58, v58
	v_fmac_f32_e32 v131, v59, v59
	v_fmac_f32_e32 v131, v60, v60
	v_fmac_f32_e32 v131, v61, v61
	v_fmac_f32_e32 v131, v62, v62
	v_fmac_f32_e32 v131, v63, v63
	v_add_f32_dpp v128, v128, v128 quad_perm:[1,0,3,2] row_mask:0xf bank_mask:0xf
	v_add_f32_dpp v129, v129, v129 quad_perm:[1,0,3,2] row_mask:0xf bank_mask:0xf
	v_add_f32_dpp v130, v130, v130 quad_perm:[1,0,3,2] row_mask:0xf bank_mask:0xf
	v_add_f32_dpp v131, v131, v131 quad_perm:[1,0,3,2] row_mask:0xf bank_mask:0xf
	v_add_f32_dpp v128, v128, v128 quad_perm:[2,3,0,1] row_mask:0xf bank_mask:0xf
	v_add_f32_dpp v129, v129, v129 quad_perm:[2,3,0,1] row_mask:0xf bank_mask:0xf
	v_add_f32_dpp v130, v130, v130 quad_perm:[2,3,0,1] row_mask:0xf bank_mask:0xf
	v_add_f32_dpp v131, v131, v131 quad_perm:[2,3,0,1] row_mask:0xf bank_mask:0xf
	v_add_f32_dpp v128, v128, v128 row_half_mirror row_mask:0xf bank_mask:0xf
	v_add_f32_dpp v129, v129, v129 row_half_mirror row_mask:0xf bank_mask:0xf
	v_add_f32_dpp v130, v130, v130 row_half_mirror row_mask:0xf bank_mask:0xf
	v_add_f32_dpp v131, v131, v131 row_half_mirror row_mask:0xf bank_mask:0xf
	v_add_f32_dpp v128, v128, v128 row_mirror row_mask:0xf bank_mask:0xf
	v_add_f32_dpp v129, v129, v129 row_mirror row_mask:0xf bank_mask:0xf
	v_add_f32_dpp v130, v130, v130 row_mirror row_mask:0xf bank_mask:0xf
	v_add_f32_dpp v131, v131, v131 row_mirror row_mask:0xf bank_mask:0xf
	s_nop 1
	v_readlane_b32 s82, v128, 0
	v_readlane_b32 s83, v128, 16
	v_readlane_b32 s84, v128, 32
	v_readlane_b32 s85, v128, 48
	s_nop 1
	v_mov_b32_e32 v132, s82
	v_add_f32_e32 v132, s83, v132
	v_add_f32_e32 v132, s84, v132
	v_add_f32_e32 v132, s85, v132
	v_readlane_b32 s82, v129, 0
	v_readlane_b32 s83, v129, 16
	v_readlane_b32 s84, v129, 32
	v_readlane_b32 s85, v129, 48
	s_nop 1
	v_mov_b32_e32 v133, s82
	v_add_f32_e32 v133, s83, v133
	v_add_f32_e32 v133, s84, v133
	v_add_f32_e32 v133, s85, v133
	v_readlane_b32 s82, v130, 0
	v_readlane_b32 s83, v130, 16
	v_readlane_b32 s84, v130, 32
	v_readlane_b32 s85, v130, 48
	s_nop 1
	v_mov_b32_e32 v134, s82
	v_add_f32_e32 v134, s83, v134
	v_add_f32_e32 v134, s84, v134
	v_add_f32_e32 v134, s85, v134
	v_readlane_b32 s82, v131, 0
	v_readlane_b32 s83, v131, 16
	v_readlane_b32 s84, v131, 32
	v_readlane_b32 s85, v131, 48
	s_nop 1
	v_mov_b32_e32 v135, s82
	v_add_f32_e32 v135, s83, v135
	v_add_f32_e32 v135, s84, v135
	v_add_f32_e32 v135, s85, v135
	s_mov_b32 s0, 0x3a800000
	v_fma_f32 v132, v132, s0, v153
	v_fma_f32 v133, v133, s0, v153
	v_fma_f32 v134, v134, s0, v153
	v_fma_f32 v135, v135, s0, v153
	v_rsq_f32_e32 v128, v132
	v_rsq_f32_e32 v129, v133
	v_rsq_f32_e32 v130, v134
	v_rsq_f32_e32 v131, v135
	v_mul_f32_e32 v0, v0, v128
	v_mul_f32_e32 v1, v1, v128
	v_mul_f32_e32 v2, v2, v128
	v_mul_f32_e32 v3, v3, v128
	v_fma_f32 v0, v0, v154, v170
	v_fma_f32 v1, v1, v155, v171
	v_fma_f32 v2, v2, v156, v172
	v_fma_f32 v3, v3, v157, v173
	v_cvt_pk_bf16_f32 v238, v0, v1
	v_cvt_pk_bf16_f32 v239, v2, v3
	global_store_dwordx2 v148, v[238:239], s[66:67]
	v_mul_f32_e32 v4, v4, v128
	v_mul_f32_e32 v5, v5, v128
	v_mul_f32_e32 v6, v6, v128
	v_mul_f32_e32 v7, v7, v128
	v_fma_f32 v4, v4, v158, v174
	v_fma_f32 v5, v5, v159, v175
	v_fma_f32 v6, v6, v160, v176
	v_fma_f32 v7, v7, v161, v177
	v_cvt_pk_bf16_f32 v240, v4, v5
	v_cvt_pk_bf16_f32 v241, v6, v7
	global_store_dwordx2 v149, v[240:241], s[66:67]
	v_mul_f32_e32 v8, v8, v128
	v_mul_f32_e32 v9, v9, v128
	v_mul_f32_e32 v10, v10, v128
	v_mul_f32_e32 v11, v11, v128
	v_fma_f32 v8, v8, v162, v178
	v_fma_f32 v9, v9, v163, v179
	v_fma_f32 v10, v10, v164, v180
	v_fma_f32 v11, v11, v165, v181
	v_cvt_pk_bf16_f32 v242, v8, v9
	v_cvt_pk_bf16_f32 v243, v10, v11
	global_store_dwordx2 v150, v[242:243], s[66:67]
	v_mul_f32_e32 v12, v12, v128
	v_mul_f32_e32 v13, v13, v128
; DI unsigned pack2(float lo, float hi) { f32x2_t v = {lo, hi}; bf16x2_t r = __builtin_convertvector(v, bf16x2_t); return __builtin_bit_cast(unsigned, r); }
; DI void phase_norm(const Params& p, int layer, int which  , int nrows) {
;     ...
;     const float* sh = mod + b9 * 6144 + (which == 0 ? 0 : 3) * 1024;
;     const float* sc = sh + 1024;
;     float4 gg[4], s4[4], h4[4];
; #pragma unroll
;     for (int i = 0; i < 4; ++i) {
;       const int col = 4 * (lane + 64 * i);
;       gg[i] = *(const float4*)(g + col); s4[i] = *(const float4*)(sc + col); h4[i] = *(const float4*)(sh + col);
;     ...
; #pragma unroll
;     for (int k = 0; k < 2; ++k) {
;       const float rstd = k == 0 ? rstd0 : rstd1;
; #pragma unroll
;       for (int i = 0; i < 4; ++i) {
;         const int col = 4 * (lane + 64 * i);
;         float y0 = v[k][i].x * rstd * gg[i].x * (1.f + s4[i].x) + h4[i].x;
;         float y1 = v[k][i].y * rstd * gg[i].y * (1.f + s4[i].y) + h4[i].y;
;         float y2 = v[k][i].z * rstd * gg[i].z * (1.f + s4[i].z) + h4[i].z;
;         float y3 = v[k][i].w * rstd * gg[i].w * (1.f + s4[i].w) + h4[i].w;
;         uint2 w; w.x = pack2(y0, y1); w.y = pack2(y2, y3);
;         *(uint2*)(H + (size_t)(row + k) * D + col) = w;
;       }
;     }
	v_mul_f32_e32 v14, v14, v128
	v_mul_f32_e32 v15, v15, v128
	v_fma_f32 v12, v12, v166, v182
	v_fma_f32 v13, v13, v167, v183
	v_fma_f32 v14, v14, v168, v184
	v_fma_f32 v15, v15, v169, v185
	v_cvt_pk_bf16_f32 v244, v12, v13
	v_cvt_pk_bf16_f32 v245, v14, v15
	global_store_dwordx2 v151, v[244:245], s[66:67]
	v_mul_f32_e32 v16, v16, v129
	v_mul_f32_e32 v17, v17, v129
	v_mul_f32_e32 v18, v18, v129
	v_mul_f32_e32 v19, v19, v129
	v_fma_f32 v16, v16, v154, v170
	v_fma_f32 v17, v17, v155, v171
	v_fma_f32 v18, v18, v156, v172
	v_fma_f32 v19, v19, v157, v173
	v_cvt_pk_bf16_f32 v246, v16, v17
	v_cvt_pk_bf16_f32 v247, v18, v19
	global_store_dwordx2 v148, v[246:247], s[66:67] offset:64
	v_mul_f32_e32 v20, v20, v129
	v_mul_f32_e32 v21, v21, v129
	v_mul_f32_e32 v22, v22, v129
	v_mul_f32_e32 v23, v23, v129
	v_fma_f32 v20, v20, v158, v174
	v_fma_f32 v21, v21, v159, v175
	v_fma_f32 v22, v22, v160, v176
	v_fma_f32 v23, v23, v161, v177
	v_cvt_pk_bf16_f32 v248, v20, v21
	v_cvt_pk_bf16_f32 v249, v22, v23
	global_store_dwordx2 v149, v[248:249], s[66:67] offset:64
	v_mul_f32_e32 v24, v24, v129
	v_mul_f32_e32 v25, v25, v129
	v_mul_f32_e32 v26, v26, v129
	v_mul_f32_e32 v27, v27, v129
	v_fma_f32 v24, v24, v162, v178
	v_fma_f32 v25, v25, v163, v179
	v_fma_f32 v26, v26, v164, v180
	v_fma_f32 v27, v27, v165, v181
	v_cvt_pk_bf16_f32 v238, v24, v25
	v_cvt_pk_bf16_f32 v239, v26, v27
	global_store_dwordx2 v150, v[238:239], s[66:67] offset:64
	v_mul_f32_e32 v28, v28, v129
	v_mul_f32_e32 v29, v29, v129
	v_mul_f32_e32 v30, v30, v129
	v_mul_f32_e32 v31, v31, v129
	v_fma_f32 v28, v28, v166, v182
	v_fma_f32 v29, v29, v167, v183
	v_fma_f32 v30, v30, v168, v184
	v_fma_f32 v31, v31, v169, v185
	v_cvt_pk_bf16_f32 v240, v28, v29
	v_cvt_pk_bf16_f32 v241, v30, v31
	global_store_dwordx2 v151, v[240:241], s[66:67] offset:64
	v_mul_f32_e32 v32, v32, v130
	v_mul_f32_e32 v33, v33, v130
	v_mul_f32_e32 v34, v34, v130
	v_mul_f32_e32 v35, v35, v130
	v_fma_f32 v32, v32, v154, v170
	v_fma_f32 v33, v33, v155, v171
	v_fma_f32 v34, v34, v156, v172
	v_fma_f32 v35, v35, v157, v173
	v_cvt_pk_bf16_f32 v242, v32, v33
	v_cvt_pk_bf16_f32 v243, v34, v35
	global_store_dwordx2 v148, v[242:243], s[66:67] offset:128
	v_mul_f32_e32 v36, v36, v130
	v_mul_f32_e32 v37, v37, v130
	v_mul_f32_e32 v38, v38, v130
	v_mul_f32_e32 v39, v39, v130
	v_fma_f32 v36, v36, v158, v174
	v_fma_f32 v37, v37, v159, v175
	v_fma_f32 v38, v38, v160, v176
	v_fma_f32 v39, v39, v161, v177
	v_cvt_pk_bf16_f32 v244, v36, v37
	v_cvt_pk_bf16_f32 v245, v38, v39
	global_store_dwordx2 v149, v[244:245], s[66:67] offset:128
	v_mul_f32_e32 v40, v40, v130
	v_mul_f32_e32 v41, v41, v130
	v_mul_f32_e32 v42, v42, v130
	v_mul_f32_e32 v43, v43, v130
	v_fma_f32 v40, v40, v162, v178
	v_fma_f32 v41, v41, v163, v179
	v_fma_f32 v42, v42, v164, v180
	v_fma_f32 v43, v43, v165, v181
	v_cvt_pk_bf16_f32 v246, v40, v41
	v_cvt_pk_bf16_f32 v247, v42, v43
	global_store_dwordx2 v150, v[246:247], s[66:67] offset:128
	v_mul_f32_e32 v44, v44, v130
	v_mul_f32_e32 v45, v45, v130
	v_mul_f32_e32 v46, v46, v130
	v_mul_f32_e32 v47, v47, v130
	v_fma_f32 v44, v44, v166, v182
	v_fma_f32 v45, v45, v167, v183
	v_fma_f32 v46, v46, v168, v184
	v_fma_f32 v47, v47, v169, v185
	v_cvt_pk_bf16_f32 v248, v44, v45
	v_cvt_pk_bf16_f32 v249, v46, v47
	global_store_dwordx2 v151, v[248:249], s[66:67] offset:128
	v_mul_f32_e32 v48, v48, v131
	v_mul_f32_e32 v49, v49, v131
	v_mul_f32_e32 v50, v50, v131
	v_mul_f32_e32 v51, v51, v131
	v_fma_f32 v48, v48, v154, v170
	v_fma_f32 v49, v49, v155, v171
	v_fma_f32 v50, v50, v156, v172
	v_fma_f32 v51, v51, v157, v173
	v_cvt_pk_bf16_f32 v238, v48, v49
	v_cvt_pk_bf16_f32 v239, v50, v51
	global_store_dwordx2 v148, v[238:239], s[66:67] offset:192
	v_mul_f32_e32 v52, v52, v131
	v_mul_f32_e32 v53, v53, v131
	v_mul_f32_e32 v54, v54, v131
	v_mul_f32_e32 v55, v55, v131
	v_fma_f32 v52, v52, v158, v174
	v_fma_f32 v53, v53, v159, v175
	v_fma_f32 v54, v54, v160, v176
	v_fma_f32 v55, v55, v161, v177
	v_cvt_pk_bf16_f32 v240, v52, v53
	v_cvt_pk_bf16_f32 v241, v54, v55
	global_store_dwordx2 v149, v[240:241], s[66:67] offset:192
	v_mul_f32_e32 v56, v56, v131
	v_mul_f32_e32 v57, v57, v131
	v_mul_f32_e32 v58, v58, v131
	v_mul_f32_e32 v59, v59, v131
	v_fma_f32 v56, v56, v162, v178
	v_fma_f32 v57, v57, v163, v179
	v_fma_f32 v58, v58, v164, v180
	v_fma_f32 v59, v59, v165, v181
	v_cvt_pk_bf16_f32 v242, v56, v57
	v_cvt_pk_bf16_f32 v243, v58, v59
	global_store_dwordx2 v150, v[242:243], s[66:67] offset:192
	v_mul_f32_e32 v60, v60, v131
	v_mul_f32_e32 v61, v61, v131
	v_mul_f32_e32 v62, v62, v131
	v_mul_f32_e32 v63, v63, v131
	v_fma_f32 v60, v60, v166, v182
	v_fma_f32 v61, v61, v167, v183
	v_fma_f32 v62, v62, v168, v184
	v_fma_f32 v63, v63, v169, v185
	v_cvt_pk_bf16_f32 v244, v60, v61
	v_cvt_pk_bf16_f32 v245, v62, v63
	global_store_dwordx2 v151, v[244:245], s[66:67] offset:192
	s_add_u32 s54, s54, 1
	s_cmp_lt_u32 s54, s78
	s_cbranch_scc0 .Lnm_done_7
	s_lshl_b32 s57, s54, 2
	s_lshr_b32 s1, s57, 12
	s_min_u32 s1, s1, 8
	s_cmp_eq_u32 s1, s79
	s_cbranch_scc1 .Lnm_same_18
	s_mov_b32 s79, s1
	s_mul_i32 s1, s1, 24576
	s_add_u32 s72, s70, s1
	s_addc_u32 s73, s71, 0
	s_add_u32 s74, s72, 0x1000
	s_addc_u32 s75, s73, 0
	global_load_dwordx4 v[154:157], v152, s[68:69] offset:0
	global_load_dwordx4 v[158:161], v152, s[68:69] offset:1024
	global_load_dwordx4 v[162:165], v152, s[68:69] offset:2048
	global_load_dwordx4 v[166:169], v152, s[68:69] offset:3072
	global_load_dwordx4 v[214:217], v152, s[74:75] offset:0
	global_load_dwordx4 v[218:221], v152, s[74:75] offset:1024
	global_load_dwordx4 v[222:225], v152, s[74:75] offset:2048
	global_load_dwordx4 v[226:229], v152, s[74:75] offset:3072
	global_load_dwordx4 v[170:173], v152, s[72:73] offset:0
	global_load_dwordx4 v[174:177], v152, s[72:73] offset:1024
	global_load_dwordx4 v[178:181], v152, s[72:73] offset:2048
	global_load_dwordx4 v[182:185], v152, s[72:73] offset:3072
	s_waitcnt vmcnt(0)
	v_add_f32_e32 v214, 1.0, v214
	v_add_f32_e32 v215, 1.0, v215
	v_add_f32_e32 v216, 1.0, v216
	v_add_f32_e32 v217, 1.0, v217
	v_add_f32_e32 v218, 1.0, v218
	v_add_f32_e32 v219, 1.0, v219
	v_add_f32_e32 v220, 1.0, v220
	v_add_f32_e32 v221, 1.0, v221
	v_add_f32_e32 v222, 1.0, v222
	v_add_f32_e32 v223, 1.0, v223
	v_add_f32_e32 v224, 1.0, v224
	v_add_f32_e32 v225, 1.0, v225
	v_add_f32_e32 v226, 1.0, v226
	v_add_f32_e32 v227, 1.0, v227
	v_add_f32_e32 v228, 1.0, v228
	v_add_f32_e32 v229, 1.0, v229
	v_mul_f32_e32 v154, v154, v214
	v_mul_f32_e32 v155, v155, v215
	v_mul_f32_e32 v156, v156, v216
	v_mul_f32_e32 v157, v157, v217
	v_mul_f32_e32 v158, v158, v218
	v_mul_f32_e32 v159, v159, v219
	v_mul_f32_e32 v160, v160, v220
	v_mul_f32_e32 v161, v161, v221
	v_mul_f32_e32 v162, v162, v222
	v_mul_f32_e32 v163, v163, v223
	v_mul_f32_e32 v164, v164, v224
	v_mul_f32_e32 v165, v165, v225
	v_mul_f32_e32 v166, v166, v226
	v_mul_f32_e32 v167, v167, v227
	v_mul_f32_e32 v168, v168, v228
	v_mul_f32_e32 v169, v169, v229

; DI void phase_norm(const Params& p, int layer, int which  , int nrows) {
;     ...
; #pragma unroll
;     for (int i = 0; i < 4; ++i) {
;       typedef float f4ld __attribute__((ext_vector_type(4)));
;       const f4ld a_ = __builtin_nontemporal_load((const f4ld*)xr0 + lane + 64 * i), b_ = __builtin_nontemporal_load((const f4ld*)xr1 + lane + 64 * i);
;       v[0][i] = make_float4(a_[0], a_[1], a_[2], a_[3]); v[1][i] = make_float4(b_[0], b_[1], b_[2], b_[3]);
;     }
.Lnm_j_24:
	global_load_dwordx4 v[0:3], v144, s[64:65] offset:0 nt
	global_load_dwordx4 v[4:7], v144, s[64:65] offset:1024 nt
	global_load_dwordx4 v[8:11], v144, s[64:65] offset:2048 nt
	global_load_dwordx4 v[12:15], v144, s[64:65] offset:3072 nt
	global_load_dwordx4 v[16:19], v145, s[64:65] offset:0 nt
	global_load_dwordx4 v[20:23], v145, s[64:65] offset:1024 nt
	global_load_dwordx4 v[24:27], v145, s[64:65] offset:2048 nt
	global_load_dwordx4 v[28:31], v145, s[64:65] offset:3072 nt
	global_load_dwordx4 v[32:35], v146, s[64:65] offset:0 nt
	global_load_dwordx4 v[36:39], v146, s[64:65] offset:1024 nt
	global_load_dwordx4 v[40:43], v146, s[64:65] offset:2048 nt
	global_load_dwordx4 v[44:47], v146, s[64:65] offset:3072 nt
	global_load_dwordx4 v[48:51], v147, s[64:65] offset:0 nt
	global_load_dwordx4 v[52:55], v147, s[64:65] offset:1024 nt
	global_load_dwordx4 v[56:59], v147, s[64:65] offset:2048 nt
	global_load_dwordx4 v[60:63], v147, s[64:65] offset:3072 nt
	s_waitcnt vmcnt(16)
	s_branch .Lnm_nj_22

; DI unsigned pack2(float lo, float hi) { f32x2_t v = {lo, hi}; bf16x2_t r = __builtin_convertvector(v, bf16x2_t); return __builtin_bit_cast(unsigned, r); }
; DI void phase_norm(const Params& p, int layer, int which  , int nrows) {
;     ...
; #pragma unroll
;     for (int i = 0; i < 4; ++i) {
;       ss0 += v[0][i].x * v[0][i].x + v[0][i].y * v[0][i].y + v[0][i].z * v[0][i].z + v[0][i].w * v[0][i].w;
;       ss1 += v[1][i].x * v[1][i].x + v[1][i].y * v[1][i].y + v[1][i].z * v[1][i].z + v[1][i].w * v[1][i].w;
;     }
;     ss0 = wave_sum(ss0); ss1 = wave_sum(ss1);
;     const float rstd0 = rsqrtf(ss0 * (1.0f / D) + 1e-6f), rstd1 = rsqrtf(ss1 * (1.0f / D) + 1e-6f);
; #pragma unroll
;     for (int k = 0; k < 2; ++k) {
;       const float rstd = k == 0 ? rstd0 : rstd1;
; #pragma unroll
;       for (int i = 0; i < 4; ++i) {
;         const int col = 4 * (lane + 64 * i);
;         float y0 = v[k][i].x * rstd * gg[i].x * (1.f + s4[i].x) + h4[i].x;
;         float y1 = v[k][i].y * rstd * gg[i].y * (1.f + s4[i].y) + h4[i].y;
;         float y2 = v[k][i].z * rstd * gg[i].z * (1.f + s4[i].z) + h4[i].z;
;         float y3 = v[k][i].w * rstd * gg[i].w * (1.f + s4[i].w) + h4[i].w;
;         uint2 w; w.x = pack2(y0, y1); w.y = pack2(y2, y3);
;         *(uint2*)(H + (size_t)(row + k) * D + col) = w;
.Lnm_nj_22:
	s_lshl_b32 s0, s57, 6
	s_add_u32 s0, s0, 0x15980000
	s_add_u32 s66, s24, s0
	s_addc_u32 s67, s25, 0
	v_mul_f32_e32 v128, v64, v64
	v_fmac_f32_e32 v128, v65, v65
	v_fmac_f32_e32 v128, v66, v66
	v_fmac_f32_e32 v128, v67, v67
	v_fmac_f32_e32 v128, v68, v68
	v_fmac_f32_e32 v128, v69, v69
	v_fmac_f32_e32 v128, v70, v70
	v_fmac_f32_e32 v128, v71, v71
	v_fmac_f32_e32 v128, v72, v72
	v_fmac_f32_e32 v128, v73, v73
	v_fmac_f32_e32 v128, v74, v74
	v_fmac_f32_e32 v128, v75, v75
	v_fmac_f32_e32 v128, v76, v76
	v_fmac_f32_e32 v128, v77, v77
	v_fmac_f32_e32 v128, v78, v78
	v_fmac_f32_e32 v128, v79, v79
	v_mul_f32_e32 v129, v80, v80
	v_fmac_f32_e32 v129, v81, v81
	v_fmac_f32_e32 v129, v82, v82
	v_fmac_f32_e32 v129, v83, v83
	v_fmac_f32_e32 v129, v84, v84
	v_fmac_f32_e32 v129, v85, v85
	v_fmac_f32_e32 v129, v86, v86
	v_fmac_f32_e32 v129, v87, v87
	v_fmac_f32_e32 v129, v88, v88
	v_fmac_f32_e32 v129, v89, v89
	v_fmac_f32_e32 v129, v90, v90
	v_fmac_f32_e32 v129, v91, v91
	v_fmac_f32_e32 v129, v92, v92
	v_fmac_f32_e32 v129, v93, v93
	v_fmac_f32_e32 v129, v94, v94
	v_fmac_f32_e32 v129, v95, v95
	v_mul_f32_e32 v130, v96, v96
	v_fmac_f32_e32 v130, v97, v97
	v_fmac_f32_e32 v130, v98, v98
	v_fmac_f32_e32 v130, v99, v99
	v_fmac_f32_e32 v130, v100, v100
	v_fmac_f32_e32 v130, v101, v101
	v_fmac_f32_e32 v130, v102, v102
	v_fmac_f32_e32 v130, v103, v103
	v_fmac_f32_e32 v130, v104, v104
	v_fmac_f32_e32 v130, v105, v105
	v_fmac_f32_e32 v130, v106, v106
	v_fmac_f32_e32 v130, v107, v107
	v_fmac_f32_e32 v130, v108, v108
	v_fmac_f32_e32 v130, v109, v109
	v_fmac_f32_e32 v130, v110, v110
	v_fmac_f32_e32 v130, v111, v111
	v_mul_f32_e32 v131, v112, v112
	v_fmac_f32_e32 v131, v113, v113
	v_fmac_f32_e32 v131, v114, v114
	v_fmac_f32_e32 v131, v115, v115
	v_fmac_f32_e32 v131, v116, v116
	v_fmac_f32_e32 v131, v117, v117
	v_fmac_f32_e32 v131, v118, v118
	v_fmac_f32_e32 v131, v119, v119
	v_fmac_f32_e32 v131, v120, v120
	v_fmac_f32_e32 v131, v121, v121
	v_fmac_f32_e32 v131, v122, v122
	v_fmac_f32_e32 v131, v123, v123
	v_fmac_f32_e32 v131, v124, v124
	v_fmac_f32_e32 v131, v125, v125
	v_fmac_f32_e32 v131, v126, v126
	v_fmac_f32_e32 v131, v127, v127
	v_add_f32_dpp v128, v128, v128 quad_perm:[1,0,3,2] row_mask:0xf bank_mask:0xf
	v_add_f32_dpp v129, v129, v129 quad_perm:[1,0,3,2] row_mask:0xf bank_mask:0xf
	v_add_f32_dpp v130, v130, v130 quad_perm:[1,0,3,2] row_mask:0xf bank_mask:0xf
	v_add_f32_dpp v131, v131, v131 quad_perm:[1,0,3,2] row_mask:0xf bank_mask:0xf
	v_add_f32_dpp v128, v128, v128 quad_perm:[2,3,0,1] row_mask:0xf bank_mask:0xf
	v_add_f32_dpp v129, v129, v129 quad_perm:[2,3,0,1] row_mask:0xf bank_mask:0xf
	v_add_f32_dpp v130, v130, v130 quad_perm:[2,3,0,1] row_mask:0xf bank_mask:0xf
	v_add_f32_dpp v131, v131, v131 quad_perm:[2,3,0,1] row_mask:0xf bank_mask:0xf
	v_add_f32_dpp v128, v128, v128 row_half_mirror row_mask:0xf bank_mask:0xf
	v_add_f32_dpp v129, v129, v129 row_half_mirror row_mask:0xf bank_mask:0xf
	v_add_f32_dpp v130, v130, v130 row_half_mirror row_mask:0xf bank_mask:0xf
	v_add_f32_dpp v131, v131, v131 row_half_mirror row_mask:0xf bank_mask:0xf
	v_add_f32_dpp v128, v128, v128 row_mirror row_mask:0xf bank_mask:0xf
	v_add_f32_dpp v129, v129, v129 row_mirror row_mask:0xf bank_mask:0xf
	v_add_f32_dpp v130, v130, v130 row_mirror row_mask:0xf bank_mask:0xf
	v_add_f32_dpp v131, v131, v131 row_mirror row_mask:0xf bank_mask:0xf
	s_nop 1
	v_readlane_b32 s82, v128, 0
	v_readlane_b32 s83, v128, 16
	v_readlane_b32 s84, v128, 32
	v_readlane_b32 s85, v128, 48
	s_nop 1
	v_mov_b32_e32 v132, s82
	v_add_f32_e32 v132, s83, v132
	v_add_f32_e32 v132, s84, v132
	v_add_f32_e32 v132, s85, v132
	v_readlane_b32 s82, v129, 0
	v_readlane_b32 s83, v129, 16
	v_readlane_b32 s84, v129, 32
	v_readlane_b32 s85, v129, 48
	s_nop 1
	v_mov_b32_e32 v133, s82
	v_add_f32_e32 v133, s83, v133
	v_add_f32_e32 v133, s84, v133
	v_add_f32_e32 v133, s85, v133
	v_readlane_b32 s82, v130, 0
	v_readlane_b32 s83, v130, 16
	v_readlane_b32 s84, v130, 32
	v_readlane_b32 s85, v130, 48
	s_nop 1
	v_mov_b32_e32 v134, s82
	v_add_f32_e32 v134, s83, v134
	v_add_f32_e32 v134, s84, v134
	v_add_f32_e32 v134, s85, v134
	v_readlane_b32 s82, v131, 0
	v_readlane_b32 s83, v131, 16
	v_readlane_b32 s84, v131, 32
	v_readlane_b32 s85, v131, 48
	s_nop 1
	v_mov_b32_e32 v135, s82
	v_add_f32_e32 v135, s83, v135
	v_add_f32_e32 v135, s84, v135
	v_add_f32_e32 v135, s85, v135
	s_mov_b32 s0, 0x3a800000
	v_fma_f32 v132, v132, s0, v153
	v_fma_f32 v133, v133, s0, v153
	v_fma_f32 v134, v134, s0, v153
	v_fma_f32 v135, v135, s0, v153
	v_rsq_f32_e32 v128, v132
	v_rsq_f32_e32 v129, v133
	v_rsq_f32_e32 v130, v134
	v_rsq_f32_e32 v131, v135
	v_mul_f32_e32 v64, v64, v128
	v_mul_f32_e32 v65, v65, v128
	v_mul_f32_e32 v66, v66, v128
	v_mul_f32_e32 v67, v67, v128
	v_fma_f32 v64, v64, v154, v170
	v_fma_f32 v65, v65, v155, v171
	v_fma_f32 v66, v66, v156, v172
	v_fma_f32 v67, v67, v157, v173
	v_cvt_pk_bf16_f32 v238, v64, v65
	v_cvt_pk_bf16_f32 v239, v66, v67
	global_store_dwordx2 v148, v[238:239], s[66:67]
	v_mul_f32_e32 v68, v68, v128
	v_mul_f32_e32 v69, v69, v128
	v_mul_f32_e32 v70, v70, v128
	v_mul_f32_e32 v71, v71, v128
	v_fma_f32 v68, v68, v158, v174
	v_fma_f32 v69, v69, v159, v175
	v_fma_f32 v70, v70, v160, v176
	v_fma_f32 v71, v71, v161, v177
	v_cvt_pk_bf16_f32 v240, v68, v69
	v_cvt_pk_bf16_f32 v241, v70, v71
	global_store_dwordx2 v149, v[240:241], s[66:67]
	v_mul_f32_e32 v72, v72, v128
	v_mul_f32_e32 v73, v73, v128
; DI unsigned pack2(float lo, float hi) { f32x2_t v = {lo, hi}; bf16x2_t r = __builtin_convertvector(v, bf16x2_t); return __builtin_bit_cast(unsigned, r); }
; DI void phase_norm(const Params& p, int layer, int which  , int nrows) {
;     ...
; #pragma unroll
;     for (int k = 0; k < 2; ++k) {
;       const float rstd = k == 0 ? rstd0 : rstd1;
; #pragma unroll
;       for (int i = 0; i < 4; ++i) {
;         const int col = 4 * (lane + 64 * i);
;         float y0 = v[k][i].x * rstd * gg[i].x * (1.f + s4[i].x) + h4[i].x;
;         float y1 = v[k][i].y * rstd * gg[i].y * (1.f + s4[i].y) + h4[i].y;
;         float y2 = v[k][i].z * rstd * gg[i].z * (1.f + s4[i].z) + h4[i].z;
;         float y3 = v[k][i].w * rstd * gg[i].w * (1.f + s4[i].w) + h4[i].w;
;         uint2 w; w.x = pack2(y0, y1); w.y = pack2(y2, y3);
;         *(uint2*)(H + (size_t)(row + k) * D + col) = w;
;       }
;     }
	v_mul_f32_e32 v74, v74, v128
	v_mul_f32_e32 v75, v75, v128
	v_fma_f32 v72, v72, v162, v178
	v_fma_f32 v73, v73, v163, v179
	v_fma_f32 v74, v74, v164, v180
	v_fma_f32 v75, v75, v165, v181
	v_cvt_pk_bf16_f32 v242, v72, v73
	v_cvt_pk_bf16_f32 v243, v74, v75
	global_store_dwordx2 v150, v[242:243], s[66:67]
	v_mul_f32_e32 v76, v76, v128
	v_mul_f32_e32 v77, v77, v128
	v_mul_f32_e32 v78, v78, v128
	v_mul_f32_e32 v79, v79, v128
	v_fma_f32 v76, v76, v166, v182
	v_fma_f32 v77, v77, v167, v183
	v_fma_f32 v78, v78, v168, v184
	v_fma_f32 v79, v79, v169, v185
	v_cvt_pk_bf16_f32 v244, v76, v77
	v_cvt_pk_bf16_f32 v245, v78, v79
	global_store_dwordx2 v151, v[244:245], s[66:67]
	v_mul_f32_e32 v80, v80, v129
	v_mul_f32_e32 v81, v81, v129
	v_mul_f32_e32 v82, v82, v129
	v_mul_f32_e32 v83, v83, v129
	v_fma_f32 v80, v80, v154, v170
	v_fma_f32 v81, v81, v155, v171
	v_fma_f32 v82, v82, v156, v172
	v_fma_f32 v83, v83, v157, v173
	v_cvt_pk_bf16_f32 v246, v80, v81
	v_cvt_pk_bf16_f32 v247, v82, v83
	global_store_dwordx2 v148, v[246:247], s[66:67] offset:64
	v_mul_f32_e32 v84, v84, v129
	v_mul_f32_e32 v85, v85, v129
	v_mul_f32_e32 v86, v86, v129
	v_mul_f32_e32 v87, v87, v129
	v_fma_f32 v84, v84, v158, v174
	v_fma_f32 v85, v85, v159, v175
	v_fma_f32 v86, v86, v160, v176
	v_fma_f32 v87, v87, v161, v177
	v_cvt_pk_bf16_f32 v248, v84, v85
	v_cvt_pk_bf16_f32 v249, v86, v87
	global_store_dwordx2 v149, v[248:249], s[66:67] offset:64
	v_mul_f32_e32 v88, v88, v129
	v_mul_f32_e32 v89, v89, v129
	v_mul_f32_e32 v90, v90, v129
	v_mul_f32_e32 v91, v91, v129
	v_fma_f32 v88, v88, v162, v178
	v_fma_f32 v89, v89, v163, v179
	v_fma_f32 v90, v90, v164, v180
	v_fma_f32 v91, v91, v165, v181
	v_cvt_pk_bf16_f32 v238, v88, v89
	v_cvt_pk_bf16_f32 v239, v90, v91
	global_store_dwordx2 v150, v[238:239], s[66:67] offset:64
	v_mul_f32_e32 v92, v92, v129
	v_mul_f32_e32 v93, v93, v129
	v_mul_f32_e32 v94, v94, v129
	v_mul_f32_e32 v95, v95, v129
	v_fma_f32 v92, v92, v166, v182
	v_fma_f32 v93, v93, v167, v183
	v_fma_f32 v94, v94, v168, v184
	v_fma_f32 v95, v95, v169, v185
	v_cvt_pk_bf16_f32 v240, v92, v93
	v_cvt_pk_bf16_f32 v241, v94, v95
	global_store_dwordx2 v151, v[240:241], s[66:67] offset:64
	v_mul_f32_e32 v96, v96, v130
	v_mul_f32_e32 v97, v97, v130
	v_mul_f32_e32 v98, v98, v130
	v_mul_f32_e32 v99, v99, v130
	v_fma_f32 v96, v96, v154, v170
	v_fma_f32 v97, v97, v155, v171
	v_fma_f32 v98, v98, v156, v172
	v_fma_f32 v99, v99, v157, v173
	v_cvt_pk_bf16_f32 v242, v96, v97
	v_cvt_pk_bf16_f32 v243, v98, v99
	global_store_dwordx2 v148, v[242:243], s[66:67] offset:128
	v_mul_f32_e32 v100, v100, v130
	v_mul_f32_e32 v101, v101, v130
	v_mul_f32_e32 v102, v102, v130
	v_mul_f32_e32 v103, v103, v130
	v_fma_f32 v100, v100, v158, v174
	v_fma_f32 v101, v101, v159, v175
	v_fma_f32 v102, v102, v160, v176
	v_fma_f32 v103, v103, v161, v177
	v_cvt_pk_bf16_f32 v244, v100, v101
	v_cvt_pk_bf16_f32 v245, v102, v103
	global_store_dwordx2 v149, v[244:245], s[66:67] offset:128
	v_mul_f32_e32 v104, v104, v130
	v_mul_f32_e32 v105, v105, v130
	v_mul_f32_e32 v106, v106, v130
	v_mul_f32_e32 v107, v107, v130
	v_fma_f32 v104, v104, v162, v178
	v_fma_f32 v105, v105, v163, v179
	v_fma_f32 v106, v106, v164, v180
	v_fma_f32 v107, v107, v165, v181
	v_cvt_pk_bf16_f32 v246, v104, v105
	v_cvt_pk_bf16_f32 v247, v106, v107
	global_store_dwordx2 v150, v[246:247], s[66:67] offset:128
	v_mul_f32_e32 v108, v108, v130
	v_mul_f32_e32 v109, v109, v130
	v_mul_f32_e32 v110, v110, v130
	v_mul_f32_e32 v111, v111, v130
	v_fma_f32 v108, v108, v166, v182
	v_fma_f32 v109, v109, v167, v183
	v_fma_f32 v110, v110, v168, v184
	v_fma_f32 v111, v111, v169, v185
	v_cvt_pk_bf16_f32 v248, v108, v109
	v_cvt_pk_bf16_f32 v249, v110, v111
	global_store_dwordx2 v151, v[248:249], s[66:67] offset:128
	v_mul_f32_e32 v112, v112, v131
	v_mul_f32_e32 v113, v113, v131
	v_mul_f32_e32 v114, v114, v131
	v_mul_f32_e32 v115, v115, v131
	v_fma_f32 v112, v112, v154, v170
	v_fma_f32 v113, v113, v155, v171
	v_fma_f32 v114, v114, v156, v172
	v_fma_f32 v115, v115, v157, v173
	v_cvt_pk_bf16_f32 v238, v112, v113
	v_cvt_pk_bf16_f32 v239, v114, v115
	global_store_dwordx2 v148, v[238:239], s[66:67] offset:192
	v_mul_f32_e32 v116, v116, v131
	v_mul_f32_e32 v117, v117, v131
	v_mul_f32_e32 v118, v118, v131
	v_mul_f32_e32 v119, v119, v131
	v_fma_f32 v116, v116, v158, v174
	v_fma_f32 v117, v117, v159, v175
	v_fma_f32 v118, v118, v160, v176
	v_fma_f32 v119, v119, v161, v177
	v_cvt_pk_bf16_f32 v240, v116, v117
	v_cvt_pk_bf16_f32 v241, v118, v119
	global_store_dwordx2 v149, v[240:241], s[66:67] offset:192
	v_mul_f32_e32 v120, v120, v131
	v_mul_f32_e32 v121, v121, v131
	v_mul_f32_e32 v122, v122, v131
	v_mul_f32_e32 v123, v123, v131
	v_fma_f32 v120, v120, v162, v178
	v_fma_f32 v121, v121, v163, v179
	v_fma_f32 v122, v122, v164, v180
	v_fma_f32 v123, v123, v165, v181
	v_cvt_pk_bf16_f32 v242, v120, v121
	v_cvt_pk_bf16_f32 v243, v122, v123
	global_store_dwordx2 v150, v[242:243], s[66:67] offset:192
	v_mul_f32_e32 v124, v124, v131
	v_mul_f32_e32 v125, v125, v131
	v_mul_f32_e32 v126, v126, v131
	v_mul_f32_e32 v127, v127, v131
	v_fma_f32 v124, v124, v166, v182
	v_fma_f32 v125, v125, v167, v183
	v_fma_f32 v126, v126, v168, v184
	v_fma_f32 v127, v127, v169, v185
	v_cvt_pk_bf16_f32 v244, v124, v125
	v_cvt_pk_bf16_f32 v245, v126, v127
	global_store_dwordx2 v151, v[244:245], s[66:67] offset:192
	s_add_u32 s54, s54, 1
	s_cmp_lt_u32 s54, s78
	s_cbranch_scc1 .Lnm_loop_10
